# W_out epilogue residual loads software-pipelined (rolling register prefetch, depth 4 row blocks)
# speedup vs baseline: 1.0038x; 1.0038x over previous
;     __device__ __forceinline__ void operator()(const f32x4 (&acc)[2][2][4][2], const pg8::Unit& u, int wr, int wc, int fr, int fq) const {
;         const int row0 = u.pm * 256 + wr * 64 + fr, col0 = u.pn * 256 + 32 * wc + 8 * fq;
; #pragma unroll
;         for (int ai = 0; ai < 2; ++ai)
; #pragma unroll
;             for (int m = 0; m < 4; ++m) {
;                 const size_t row = (size_t)(row0 + ai * 128 + m * 16);
;                 float rstd = 1.f, ss = 0.f;
;                 if (MODE == 4) { const GAS f32x4* sp = (const GAS f32x4*)(SSR + row * 16); f32x4 s = (sp[0] + sp[1]) + (sp[2] + sp[3]);
;                     rstd = __builtin_amdgcn_rsqf(((s[0] + s[1]) + (s[2] + s[3])) * (1.f / 1024.f) + EPS); }
; #pragma unroll
;                 for (int bj = 0; bj < 2; ++bj) {
;                     const size_t off = row * 1024 + col0 + 128 * bj;
;                     const f32x4 a0 = acc[ai][bj][m][0], a1 = acc[ai][bj][m][1];
;                     if (MODE == 0) { f32x4 g0, g1; h8_to_f(*(const GAS h8*)(G16 + off), g0, g1); *(GAS h8*)(O16 + off) = pack8(g0 * a0, g1 * a1); }
;                     if (MODE == 1) { f32x4 g0, g1, p0, p1; h8_to_f(*(const GAS h8*)(G16 + off), g0, g1); h8_to_f(*(const GAS h8*)(O16 + off), p0, p1); *(GAS h8*)(O16 + off) = pack8(p0 + g0 * a0, p1 + g1 * a1); }
;                     if (MODE == 2) { const f32x4 x0 = __builtin_nontemporal_load((const GAS f32x4*)(RES + off)) + a0, x1 = __builtin_nontemporal_load((const GAS f32x4*)(RES + off + 4)) + a1;
;                         *(GAS h8*)(O16 + off) = pack8(x0, x1); ss += sq4(x0) + sq4(x1); }
;                     if (MODE == 5) { f32x4 r0, r1; h8_to_f(*(const GAS h8*)(R16 + off), r0, r1); const f32x4 x0 = r0 + a0, x1 = r1 + a1;
;                         *(GAS h8*)(O16 + off) = pack8(x0, x1); ss += sq4(x0) + sq4(x1); }
;                     if (MODE == 3) { *(GAS h8*)(O16 + off) = pack8(a0, a1); }
;                     if (MODE == 4) { f32x4 g0, g1; h8_to_f(*(const GAS h8*)(G16 + off), g0, g1);
;                         f32x4 r0, r1; h8_to_f(*(const GAS h8*)(R16 + off), r0, r1);
;                         const f32x4 x0 = r0 + sigm4(a0 * rstd) * g0, x1 = r1 + sigm4(a1 * rstd) * g1;
;                         __builtin_nontemporal_store(x0, (GAS f32x4*)(OUT + off)); __builtin_nontemporal_store(x1, (GAS f32x4*)(OUT + off + 4)); }
;                 }
.LBB0_900:
	s_waitcnt lgkmcnt(0)
	v_lshl_add_u32 v146, s66, 8, v148
	v_lshl_add_u32 v144, s24, 8, v150
	v_ashrrev_i32_e32 v147, 31, v146
	v_ashrrev_i32_e32 v145, 31, v144
	v_lshlrev_b64 v[154:155], 10, v[146:147]
	v_lshl_add_u64 v[156:157], v[154:155], 0, v[144:145]
	v_lshl_add_u64 v[234:235], v[156:157], 2, s[18:19]
	v_lshl_add_u32 v158, s66, 8, v148
	v_lshl_add_u32 v156, s24, 8, v150
	v_ashrrev_i32_e32 v157, 31, v156
	v_or_b32_e32 v144, 16, v158
	v_ashrrev_i32_e32 v145, 31, v144
	v_lshlrev_b64 v[146:147], 10, v[144:145]
	v_lshl_add_u64 v[154:155], v[146:147], 0, v[156:157]
	v_lshl_add_u64 v[236:237], v[154:155], 2, s[18:19]
	v_lshl_add_u32 v158, s66, 8, v148
	v_lshl_add_u32 v156, s24, 8, v150
	v_ashrrev_i32_e32 v157, 31, v156
	v_or_b32_e32 v144, 32, v158
	v_ashrrev_i32_e32 v145, 31, v144
	v_lshlrev_b64 v[146:147], 10, v[144:145]
	v_lshl_add_u64 v[154:155], v[146:147], 0, v[156:157]
	v_lshl_add_u64 v[238:239], v[154:155], 2, s[18:19]
	v_lshl_add_u32 v158, s66, 8, v148
	v_lshl_add_u32 v156, s24, 8, v150
	v_ashrrev_i32_e32 v157, 31, v156
	v_or_b32_e32 v144, 48, v158
	v_ashrrev_i32_e32 v145, 31, v144
	v_lshlrev_b64 v[146:147], 10, v[144:145]
	v_lshl_add_u64 v[154:155], v[146:147], 0, v[156:157]
	v_lshl_add_u64 v[240:241], v[154:155], 2, s[18:19]
	v_lshl_add_u32 v158, s66, 8, v148
	v_lshl_add_u32 v156, s24, 8, v150
	v_ashrrev_i32_e32 v157, 31, v156
	v_add_u32_e32 v144, 0x80, v158
	v_ashrrev_i32_e32 v145, 31, v144
	v_lshlrev_b64 v[146:147], 10, v[144:145]
	v_lshl_add_u64 v[154:155], v[146:147], 0, v[156:157]
	v_lshl_add_u64 v[242:243], v[154:155], 2, s[18:19]
	v_lshl_add_u32 v158, s66, 8, v148
	v_lshl_add_u32 v156, s24, 8, v150
	v_ashrrev_i32_e32 v157, 31, v156
	v_add_u32_e32 v144, 0x90, v158
	v_ashrrev_i32_e32 v145, 31, v144
	v_lshlrev_b64 v[146:147], 10, v[144:145]
	v_lshl_add_u64 v[154:155], v[146:147], 0, v[156:157]
	v_lshl_add_u64 v[244:245], v[154:155], 2, s[18:19]
	v_lshl_add_u32 v158, s66, 8, v148
	v_lshl_add_u32 v156, s24, 8, v150
	v_ashrrev_i32_e32 v157, 31, v156
	v_add_u32_e32 v144, 0xa0, v158
	v_ashrrev_i32_e32 v145, 31, v144
	v_lshlrev_b64 v[146:147], 10, v[144:145]
	v_lshl_add_u64 v[154:155], v[146:147], 0, v[156:157]
	v_lshl_add_u64 v[246:247], v[154:155], 2, s[18:19]
	v_lshl_add_u32 v158, s66, 8, v148
	v_lshl_add_u32 v156, s24, 8, v150
	v_ashrrev_i32_e32 v157, 31, v156
	v_add_u32_e32 v144, 0xb0, v158
	v_ashrrev_i32_e32 v145, 31, v144
	v_lshlrev_b64 v[146:147], 10, v[144:145]
	v_lshl_add_u64 v[154:155], v[146:147], 0, v[156:157]
	v_lshl_add_u64 v[250:251], v[154:155], 2, s[18:19]
	global_load_dwordx4 v[166:169], v[234:235], off nt
	global_load_dwordx4 v[170:173], v[234:235], off offset:16 nt
	global_load_dwordx4 v[178:181], v[234:235], off offset:512 nt
	global_load_dwordx4 v[182:185], v[234:235], off offset:528 nt
	global_load_dwordx4 v[186:189], v[236:237], off nt
	global_load_dwordx4 v[190:193], v[236:237], off offset:16 nt
	global_load_dwordx4 v[194:197], v[236:237], off offset:512 nt
	global_load_dwordx4 v[198:201], v[236:237], off offset:528 nt
	global_load_dwordx4 v[202:205], v[238:239], off nt
	global_load_dwordx4 v[206:209], v[238:239], off offset:16 nt
	global_load_dwordx4 v[210:213], v[238:239], off offset:512 nt
	global_load_dwordx4 v[214:217], v[238:239], off offset:528 nt
	global_load_dwordx4 v[218:221], v[240:241], off nt
	global_load_dwordx4 v[222:225], v[240:241], off offset:16 nt
	global_load_dwordx4 v[226:229], v[240:241], off offset:512 nt
	global_load_dwordx4 v[230:233], v[240:241], off offset:528 nt
	s_and_b64 vcc, exec, s[48:49]
	s_cbranch_vccz .LBB0_902
	s_barrier
.LBB0_902:
	v_lshl_add_u32 v146, s66, 8, v148
	v_lshl_add_u32 v144, s24, 8, v150
	v_ashrrev_i32_e32 v147, 31, v146
	v_ashrrev_i32_e32 v145, 31, v144
	v_lshlrev_b64 v[154:155], 10, v[146:147]
	v_lshl_add_u64 v[162:163], v[154:155], 0, v[144:145]
	s_waitcnt lgkmcnt(0)
	v_lshl_add_u64 v[164:165], v[162:163], 2, s[18:19]
	s_waitcnt vmcnt(12)
	s_nop 1
	v_mov_b64_e32 v[154:155], v[166:167]
	v_mov_b64_e32 v[156:157], v[168:169]
	s_nop 1
	v_mov_b64_e32 v[158:159], v[170:171]
	v_mov_b64_e32 v[160:161], v[172:173]
	v_lshl_add_u64 v[162:163], v[162:163], 1, s[40:41]
	s_lshl_b32 s52, s24, 2
	s_ashr_i32 s53, s52, 31
	v_pk_add_f32 v[156:157], v[122:123], v[156:157]
	v_pk_add_f32 v[154:155], v[120:121], v[154:155]
	v_pk_add_f32 v[160:161], v[126:127], v[160:161]
	v_pk_add_f32 v[158:159], v[124:125], v[158:159]
	v_cvt_pk_f16_f32 v123, v160, v161
	v_cvt_pk_f16_f32 v121, v156, v157
	v_cvt_pk_f16_f32 v122, v158, v159
	v_cvt_pk_f16_f32 v120, v154, v155
	global_store_dwordx4 v[162:163], v[120:123], off
	s_nop 1
	v_mov_b64_e32 v[120:121], v[178:179]
	v_mov_b64_e32 v[122:123], v[180:181]
	s_nop 0
	s_nop 1
	v_mov_b64_e32 v[124:125], v[182:183]
	v_mov_b64_e32 v[126:127], v[184:185]
	global_load_dwordx4 v[166:169], v[242:243], off nt
	global_load_dwordx4 v[170:173], v[242:243], off offset:16 nt
	global_load_dwordx4 v[178:181], v[242:243], off offset:512 nt
	global_load_dwordx4 v[182:185], v[242:243], off offset:528 nt
	v_mul_f32_e32 v155, v155, v155
	v_mul_f32_e32 v157, v157, v157
	v_mul_f32_e32 v159, v159, v159
	v_mul_f32_e32 v161, v161, v161
	v_fmac_f32_e32 v155, v154, v154
	v_fmac_f32_e32 v157, v156, v156
	v_fmac_f32_e32 v159, v158, v158
	v_fmac_f32_e32 v161, v160, v160
	v_add_f32_e32 v154, v155, v157
	v_add_f32_e32 v155, v159, v161
	v_add_f32_e32 v154, v154, v155
	v_pk_add_f32 v[118:119], v[118:119], v[122:123]
	v_pk_add_f32 v[120:121], v[116:117], v[120:121]
	v_pk_add_f32 v[114:115], v[114:115], v[126:127]
	v_pk_add_f32 v[122:123], v[112:113], v[124:125]
	v_mul_f32_e32 v112, v121, v121
	v_mul_f32_e32 v113, v119, v119
	v_mul_f32_e32 v116, v123, v123
	v_mul_f32_e32 v117, v115, v115
	v_fmac_f32_e32 v112, v120, v120
	v_fmac_f32_e32 v113, v118, v118
	v_fmac_f32_e32 v116, v122, v122
	v_fmac_f32_e32 v117, v114, v114
	v_add_f32_e32 v112, v112, v113
	v_add_f32_e32 v113, v116, v117
	v_add_f32_e32 v112, v112, v113
	v_add_f32_e32 v112, v154, v112
	ds_bpermute_b32 v113, v175, v112
	v_cvt_pk_f16_f32 v117, v114, v115
	v_cvt_pk_f16_f32 v115, v118, v119
	v_cvt_pk_f16_f32 v116, v122, v123
	v_cvt_pk_f16_f32 v114, v120, v121
	s_waitcnt lgkmcnt(0)
	v_add_f32_e32 v112, v112, v113
	ds_bpermute_b32 v113, v177, v112
	global_store_dwordx4 v[162:163], v[114:117], off offset:256
	s_and_saveexec_b64 s[54:55], s[10:11]
	s_cbranch_execz .LBB0_904
	v_lshlrev_b64 v[114:115], 6, v[146:147]
	v_lshl_add_u64 v[114:115], s[16:17], 0, v[114:115]
	v_lshl_add_u64 v[114:115], s[52:53], 2, v[114:115]
	s_lshl_b32 s24, s80, 2
	v_lshl_add_u64 v[114:115], v[114:115], 0, s[24:25]
	s_waitcnt lgkmcnt(0)
	v_add_f32_e32 v112, v112, v113
	global_store_dword v[114:115], v112, off
;     __device__ __forceinline__ void operator()(const f32x4 (&acc)[2][2][4][2], const pg8::Unit& u, int wr, int wc, int fr, int fq) const {
;         const int row0 = u.pm * 256 + wr * 64 + fr, col0 = u.pn * 256 + 32 * wc + 8 * fq;
; #pragma unroll
;         for (int ai = 0; ai < 2; ++ai)
; #pragma unroll
;             for (int m = 0; m < 4; ++m) {
;                 const size_t row = (size_t)(row0 + ai * 128 + m * 16);
;                 float rstd = 1.f, ss = 0.f;
;                 if (MODE == 4) { const GAS f32x4* sp = (const GAS f32x4*)(SSR + row * 16); f32x4 s = (sp[0] + sp[1]) + (sp[2] + sp[3]);
;                     rstd = __builtin_amdgcn_rsqf(((s[0] + s[1]) + (s[2] + s[3])) * (1.f / 1024.f) + EPS); }
; #pragma unroll
;                 for (int bj = 0; bj < 2; ++bj) {
;                     const size_t off = row * 1024 + col0 + 128 * bj;
;                     const f32x4 a0 = acc[ai][bj][m][0], a1 = acc[ai][bj][m][1];
;                     if (MODE == 0) { f32x4 g0, g1; h8_to_f(*(const GAS h8*)(G16 + off), g0, g1); *(GAS h8*)(O16 + off) = pack8(g0 * a0, g1 * a1); }
;                     if (MODE == 1) { f32x4 g0, g1, p0, p1; h8_to_f(*(const GAS h8*)(G16 + off), g0, g1); h8_to_f(*(const GAS h8*)(O16 + off), p0, p1); *(GAS h8*)(O16 + off) = pack8(p0 + g0 * a0, p1 + g1 * a1); }
;                     if (MODE == 2) { const f32x4 x0 = __builtin_nontemporal_load((const GAS f32x4*)(RES + off)) + a0, x1 = __builtin_nontemporal_load((const GAS f32x4*)(RES + off + 4)) + a1;
;                         *(GAS h8*)(O16 + off) = pack8(x0, x1); ss += sq4(x0) + sq4(x1); }
;                     if (MODE == 5) { f32x4 r0, r1; h8_to_f(*(const GAS h8*)(R16 + off), r0, r1); const f32x4 x0 = r0 + a0, x1 = r1 + a1;
;                         *(GAS h8*)(O16 + off) = pack8(x0, x1); ss += sq4(x0) + sq4(x1); }
;                     if (MODE == 3) { *(GAS h8*)(O16 + off) = pack8(a0, a1); }
;                     if (MODE == 4) { f32x4 g0, g1; h8_to_f(*(const GAS h8*)(G16 + off), g0, g1);
;                         f32x4 r0, r1; h8_to_f(*(const GAS h8*)(R16 + off), r0, r1);
;                         const f32x4 x0 = r0 + sigm4(a0 * rstd) * g0, x1 = r1 + sigm4(a1 * rstd) * g1;
;                         __builtin_nontemporal_store(x0, (GAS f32x4*)(OUT + off)); __builtin_nontemporal_store(x1, (GAS f32x4*)(OUT + off + 4)); }
;                 }
.LBB0_904:
	s_or_b64 exec, exec, s[54:55]
	v_or_b32_e32 v112, 16, v146
	s_waitcnt lgkmcnt(0)
	v_ashrrev_i32_e32 v113, 31, v112
	v_lshlrev_b64 v[114:115], 10, v[112:113]
	v_lshl_add_u64 v[122:123], v[114:115], 0, v[144:145]
	v_lshl_add_u64 v[124:125], v[122:123], 2, s[18:19]
	s_waitcnt vmcnt(12)
	s_nop 1
	v_mov_b64_e32 v[114:115], v[186:187]
	v_mov_b64_e32 v[116:117], v[188:189]
	s_nop 1
	v_mov_b64_e32 v[118:119], v[190:191]
	v_mov_b64_e32 v[120:121], v[192:193]
	v_lshl_add_u64 v[122:123], v[122:123], 1, s[40:41]
	v_pk_add_f32 v[116:117], v[110:111], v[116:117]
	v_pk_add_f32 v[114:115], v[108:109], v[114:115]
	v_pk_add_f32 v[120:121], v[106:107], v[120:121]
	v_pk_add_f32 v[118:119], v[104:105], v[118:119]
	v_cvt_pk_f16_f32 v107, v120, v121
	v_cvt_pk_f16_f32 v105, v116, v117
	v_cvt_pk_f16_f32 v106, v118, v119
	v_cvt_pk_f16_f32 v104, v114, v115
	global_store_dwordx4 v[122:123], v[104:107], off
	s_nop 1
	v_mov_b64_e32 v[104:105], v[194:195]
	v_mov_b64_e32 v[106:107], v[196:197]
	s_nop 0
	s_nop 1
	v_mov_b64_e32 v[108:109], v[198:199]
	v_mov_b64_e32 v[110:111], v[200:201]
	global_load_dwordx4 v[186:189], v[244:245], off nt
	global_load_dwordx4 v[190:193], v[244:245], off offset:16 nt
	global_load_dwordx4 v[194:197], v[244:245], off offset:512 nt
	global_load_dwordx4 v[198:201], v[244:245], off offset:528 nt
	v_mul_f32_e32 v115, v115, v115
	v_mul_f32_e32 v117, v117, v117
	v_mul_f32_e32 v119, v119, v119
	v_mul_f32_e32 v121, v121, v121
	v_fmac_f32_e32 v115, v114, v114
	v_fmac_f32_e32 v117, v116, v116
	v_fmac_f32_e32 v119, v118, v118
	v_fmac_f32_e32 v121, v120, v120
	v_add_f32_e32 v114, v115, v117
	v_add_f32_e32 v115, v119, v121
	v_add_f32_e32 v114, v114, v115
	v_pk_add_f32 v[102:103], v[102:103], v[106:107]
	v_pk_add_f32 v[104:105], v[100:101], v[104:105]
	v_pk_add_f32 v[98:99], v[98:99], v[110:111]
	v_pk_add_f32 v[106:107], v[96:97], v[108:109]
	v_mul_f32_e32 v96, v105, v105
	v_mul_f32_e32 v97, v103, v103
	v_mul_f32_e32 v100, v107, v107
	v_mul_f32_e32 v101, v99, v99
	v_fmac_f32_e32 v96, v104, v104
	v_fmac_f32_e32 v97, v102, v102
	v_fmac_f32_e32 v100, v106, v106
	v_fmac_f32_e32 v101, v98, v98
	v_add_f32_e32 v96, v96, v97
	v_add_f32_e32 v97, v100, v101
	v_add_f32_e32 v96, v96, v97
	v_add_f32_e32 v96, v114, v96
	ds_bpermute_b32 v97, v175, v96
	v_cvt_pk_f16_f32 v101, v98, v99
	v_cvt_pk_f16_f32 v99, v102, v103
	v_cvt_pk_f16_f32 v100, v106, v107
	v_cvt_pk_f16_f32 v98, v104, v105
	s_waitcnt lgkmcnt(0)
	v_add_f32_e32 v96, v96, v97
	ds_bpermute_b32 v97, v177, v96
	global_store_dwordx4 v[122:123], v[98:101], off offset:256
	s_and_saveexec_b64 s[54:55], s[10:11]
	s_cbranch_execz .LBB0_906
	v_lshlrev_b64 v[98:99], 6, v[112:113]
	v_lshl_add_u64 v[98:99], s[16:17], 0, v[98:99]
	v_lshl_add_u64 v[98:99], s[52:53], 2, v[98:99]
	s_lshl_b32 s24, s80, 2
	v_lshl_add_u64 v[98:99], v[98:99], 0, s[24:25]
	s_waitcnt lgkmcnt(0)
	v_add_f32_e32 v96, v96, v97
	global_store_dword v[98:99], v96, off
.LBB0_906:
	s_or_b64 exec, exec, s[54:55]
	v_or_b32_e32 v96, 32, v146
	s_waitcnt lgkmcnt(0)
	v_ashrrev_i32_e32 v97, 31, v96
	v_lshlrev_b64 v[98:99], 10, v[96:97]
	v_lshl_add_u64 v[106:107], v[98:99], 0, v[144:145]
	v_lshl_add_u64 v[108:109], v[106:107], 2, s[18:19]
	s_waitcnt vmcnt(12)
	s_nop 1
	v_mov_b64_e32 v[98:99], v[202:203]
	v_mov_b64_e32 v[100:101], v[204:205]
	s_nop 1
	v_mov_b64_e32 v[102:103], v[206:207]
	v_mov_b64_e32 v[104:105], v[208:209]
	v_lshl_add_u64 v[106:107], v[106:107], 1, s[40:41]
	v_pk_add_f32 v[100:101], v[94:95], v[100:101]
	v_pk_add_f32 v[98:99], v[92:93], v[98:99]
	v_pk_add_f32 v[104:105], v[90:91], v[104:105]
	v_pk_add_f32 v[102:103], v[88:89], v[102:103]
	v_cvt_pk_f16_f32 v91, v104, v105
	v_cvt_pk_f16_f32 v89, v100, v101
	v_cvt_pk_f16_f32 v90, v102, v103
	v_cvt_pk_f16_f32 v88, v98, v99
	global_store_dwordx4 v[106:107], v[88:91], off
	s_nop 1
	v_mov_b64_e32 v[88:89], v[210:211]
	v_mov_b64_e32 v[90:91], v[212:213]
	s_nop 0
	s_nop 1
	v_mov_b64_e32 v[92:93], v[214:215]
	v_mov_b64_e32 v[94:95], v[216:217]
	global_load_dwordx4 v[202:205], v[246:247], off nt
	global_load_dwordx4 v[206:209], v[246:247], off offset:16 nt
	global_load_dwordx4 v[210:213], v[246:247], off offset:512 nt
	global_load_dwordx4 v[214:217], v[246:247], off offset:528 nt
	v_mul_f32_e32 v99, v99, v99
	v_mul_f32_e32 v101, v101, v101
	v_mul_f32_e32 v103, v103, v103
	v_mul_f32_e32 v105, v105, v105
	v_fmac_f32_e32 v99, v98, v98
	v_fmac_f32_e32 v101, v100, v100
	v_fmac_f32_e32 v103, v102, v102
	v_fmac_f32_e32 v105, v104, v104
	v_add_f32_e32 v98, v99, v101
	v_add_f32_e32 v99, v103, v105
	v_add_f32_e32 v98, v98, v99
	v_pk_add_f32 v[86:87], v[86:87], v[90:91]
	v_pk_add_f32 v[88:89], v[84:85], v[88:89]
	v_pk_add_f32 v[82:83], v[82:83], v[94:95]
	v_pk_add_f32 v[90:91], v[80:81], v[92:93]
	v_mul_f32_e32 v80, v89, v89
	v_mul_f32_e32 v81, v87, v87
	v_mul_f32_e32 v84, v91, v91
	v_mul_f32_e32 v85, v83, v83
	v_fmac_f32_e32 v80, v88, v88
	v_fmac_f32_e32 v81, v86, v86
	v_fmac_f32_e32 v84, v90, v90
	v_fmac_f32_e32 v85, v82, v82
	v_add_f32_e32 v80, v80, v81
	v_add_f32_e32 v81, v84, v85
	v_add_f32_e32 v80, v80, v81
	v_add_f32_e32 v80, v98, v80
	ds_bpermute_b32 v81, v175, v80
	v_cvt_pk_f16_f32 v85, v82, v83
	v_cvt_pk_f16_f32 v83, v86, v87
	v_cvt_pk_f16_f32 v84, v90, v91
	v_cvt_pk_f16_f32 v82, v88, v89
	s_waitcnt lgkmcnt(0)
	v_add_f32_e32 v80, v80, v81
	ds_bpermute_b32 v81, v177, v80
	global_store_dwordx4 v[106:107], v[82:85], off offset:256
	s_and_saveexec_b64 s[54:55], s[10:11]
	s_cbranch_execz .LBB0_908
	v_lshlrev_b64 v[82:83], 6, v[96:97]
	v_lshl_add_u64 v[82:83], s[16:17], 0, v[82:83]
	v_lshl_add_u64 v[82:83], s[52:53], 2, v[82:83]
	s_lshl_b32 s24, s80, 2
	v_lshl_add_u64 v[82:83], v[82:83], 0, s[24:25]
	s_waitcnt lgkmcnt(0)
	v_add_f32_e32 v80, v80, v81
	global_store_dword v[82:83], v80, off
;     __device__ __forceinline__ void operator()(const f32x4 (&acc)[2][2][4][2], const pg8::Unit& u, int wr, int wc, int fr, int fq) const {
;         const int row0 = u.pm * 256 + wr * 64 + fr, col0 = u.pn * 256 + 32 * wc + 8 * fq;
; #pragma unroll
;         for (int ai = 0; ai < 2; ++ai)
; #pragma unroll
;             for (int m = 0; m < 4; ++m) {
;                 const size_t row = (size_t)(row0 + ai * 128 + m * 16);
;                 float rstd = 1.f, ss = 0.f;
;                 if (MODE == 4) { const GAS f32x4* sp = (const GAS f32x4*)(SSR + row * 16); f32x4 s = (sp[0] + sp[1]) + (sp[2] + sp[3]);
;                     rstd = __builtin_amdgcn_rsqf(((s[0] + s[1]) + (s[2] + s[3])) * (1.f / 1024.f) + EPS); }
; #pragma unroll
;                 for (int bj = 0; bj < 2; ++bj) {
;                     const size_t off = row * 1024 + col0 + 128 * bj;
;                     const f32x4 a0 = acc[ai][bj][m][0], a1 = acc[ai][bj][m][1];
;                     if (MODE == 0) { f32x4 g0, g1; h8_to_f(*(const GAS h8*)(G16 + off), g0, g1); *(GAS h8*)(O16 + off) = pack8(g0 * a0, g1 * a1); }
;                     if (MODE == 1) { f32x4 g0, g1, p0, p1; h8_to_f(*(const GAS h8*)(G16 + off), g0, g1); h8_to_f(*(const GAS h8*)(O16 + off), p0, p1); *(GAS h8*)(O16 + off) = pack8(p0 + g0 * a0, p1 + g1 * a1); }
;                     if (MODE == 2) { const f32x4 x0 = __builtin_nontemporal_load((const GAS f32x4*)(RES + off)) + a0, x1 = __builtin_nontemporal_load((const GAS f32x4*)(RES + off + 4)) + a1;
;                         *(GAS h8*)(O16 + off) = pack8(x0, x1); ss += sq4(x0) + sq4(x1); }
;                     if (MODE == 5) { f32x4 r0, r1; h8_to_f(*(const GAS h8*)(R16 + off), r0, r1); const f32x4 x0 = r0 + a0, x1 = r1 + a1;
;                         *(GAS h8*)(O16 + off) = pack8(x0, x1); ss += sq4(x0) + sq4(x1); }
;                     if (MODE == 3) { *(GAS h8*)(O16 + off) = pack8(a0, a1); }
;                     if (MODE == 4) { f32x4 g0, g1; h8_to_f(*(const GAS h8*)(G16 + off), g0, g1);
;                         f32x4 r0, r1; h8_to_f(*(const GAS h8*)(R16 + off), r0, r1);
;                         const f32x4 x0 = r0 + sigm4(a0 * rstd) * g0, x1 = r1 + sigm4(a1 * rstd) * g1;
;                         __builtin_nontemporal_store(x0, (GAS f32x4*)(OUT + off)); __builtin_nontemporal_store(x1, (GAS f32x4*)(OUT + off + 4)); }
;                 }
.LBB0_908:
	s_or_b64 exec, exec, s[54:55]
	v_or_b32_e32 v80, 48, v146
	s_waitcnt lgkmcnt(0)
	v_ashrrev_i32_e32 v81, 31, v80
	v_lshlrev_b64 v[82:83], 10, v[80:81]
	v_lshl_add_u64 v[90:91], v[82:83], 0, v[144:145]
	v_lshl_add_u64 v[92:93], v[90:91], 2, s[18:19]
	s_waitcnt vmcnt(12)
	s_nop 1
	v_mov_b64_e32 v[82:83], v[218:219]
	v_mov_b64_e32 v[84:85], v[220:221]
	s_nop 1
	v_mov_b64_e32 v[86:87], v[222:223]
	v_mov_b64_e32 v[88:89], v[224:225]
	v_lshl_add_u64 v[90:91], v[90:91], 1, s[40:41]
	v_pk_add_f32 v[84:85], v[78:79], v[84:85]
	v_pk_add_f32 v[82:83], v[76:77], v[82:83]
	v_pk_add_f32 v[88:89], v[74:75], v[88:89]
	v_pk_add_f32 v[86:87], v[72:73], v[86:87]
	v_cvt_pk_f16_f32 v75, v88, v89
	v_cvt_pk_f16_f32 v73, v84, v85
	v_cvt_pk_f16_f32 v74, v86, v87
	v_cvt_pk_f16_f32 v72, v82, v83
	global_store_dwordx4 v[90:91], v[72:75], off
	s_nop 1
	v_mov_b64_e32 v[72:73], v[226:227]
	v_mov_b64_e32 v[74:75], v[228:229]
	s_nop 0
	s_nop 1
	v_mov_b64_e32 v[76:77], v[230:231]
	v_mov_b64_e32 v[78:79], v[232:233]
	global_load_dwordx4 v[218:221], v[250:251], off nt
	global_load_dwordx4 v[222:225], v[250:251], off offset:16 nt
	global_load_dwordx4 v[226:229], v[250:251], off offset:512 nt
	global_load_dwordx4 v[230:233], v[250:251], off offset:528 nt
	v_mul_f32_e32 v83, v83, v83
	v_mul_f32_e32 v85, v85, v85
	v_mul_f32_e32 v87, v87, v87
	v_mul_f32_e32 v89, v89, v89
	v_fmac_f32_e32 v83, v82, v82
	v_fmac_f32_e32 v85, v84, v84
	v_fmac_f32_e32 v87, v86, v86
	v_fmac_f32_e32 v89, v88, v88
	v_add_f32_e32 v82, v83, v85
	v_add_f32_e32 v83, v87, v89
	v_add_f32_e32 v82, v82, v83
	v_pk_add_f32 v[70:71], v[70:71], v[74:75]
	v_pk_add_f32 v[72:73], v[68:69], v[72:73]
	v_pk_add_f32 v[66:67], v[66:67], v[78:79]
	v_pk_add_f32 v[74:75], v[64:65], v[76:77]
	v_mul_f32_e32 v64, v73, v73
	v_mul_f32_e32 v65, v71, v71
	v_mul_f32_e32 v68, v75, v75
	v_mul_f32_e32 v69, v67, v67
	v_fmac_f32_e32 v64, v72, v72
	v_fmac_f32_e32 v65, v70, v70
	v_fmac_f32_e32 v68, v74, v74
	v_fmac_f32_e32 v69, v66, v66
	v_add_f32_e32 v64, v64, v65
	v_add_f32_e32 v65, v68, v69
	v_add_f32_e32 v64, v64, v65
	v_add_f32_e32 v64, v82, v64
	ds_bpermute_b32 v65, v175, v64
	v_cvt_pk_f16_f32 v69, v66, v67
	v_cvt_pk_f16_f32 v67, v70, v71
	v_cvt_pk_f16_f32 v68, v74, v75
	v_cvt_pk_f16_f32 v66, v72, v73
	s_waitcnt lgkmcnt(0)
	v_add_f32_e32 v64, v64, v65
	ds_bpermute_b32 v65, v177, v64
	global_store_dwordx4 v[90:91], v[66:69], off offset:256
	s_and_saveexec_b64 s[54:55], s[10:11]
	s_cbranch_execz .LBB0_910
	v_lshlrev_b64 v[66:67], 6, v[80:81]
	v_lshl_add_u64 v[66:67], s[16:17], 0, v[66:67]
	v_lshl_add_u64 v[66:67], s[52:53], 2, v[66:67]
	s_lshl_b32 s24, s80, 2
	v_lshl_add_u64 v[66:67], v[66:67], 0, s[24:25]
	s_waitcnt lgkmcnt(0)
	v_add_f32_e32 v64, v64, v65
	global_store_dword v[66:67], v64, off
.LBB0_910:
	s_or_b64 exec, exec, s[54:55]
	v_add_u32_e32 v64, 0x80, v146
	s_waitcnt lgkmcnt(0)
	v_ashrrev_i32_e32 v65, 31, v64
	v_lshlrev_b64 v[66:67], 10, v[64:65]
	v_lshl_add_u64 v[74:75], v[66:67], 0, v[144:145]
	v_lshl_add_u64 v[76:77], v[74:75], 2, s[18:19]
	s_waitcnt vmcnt(12)
	s_nop 1
	v_mov_b64_e32 v[66:67], v[166:167]
	v_mov_b64_e32 v[68:69], v[168:169]
	s_nop 1
	v_mov_b64_e32 v[70:71], v[170:171]
	v_mov_b64_e32 v[72:73], v[172:173]
	v_lshl_add_u64 v[74:75], v[74:75], 1, s[40:41]
	v_pk_add_f32 v[68:69], v[62:63], v[68:69]
	v_pk_add_f32 v[66:67], v[60:61], v[66:67]
	v_pk_add_f32 v[72:73], v[58:59], v[72:73]
	v_pk_add_f32 v[70:71], v[56:57], v[70:71]
	v_cvt_pk_f16_f32 v59, v72, v73
	v_cvt_pk_f16_f32 v57, v68, v69
	v_cvt_pk_f16_f32 v58, v70, v71
	v_cvt_pk_f16_f32 v56, v66, v67
	global_store_dwordx4 v[74:75], v[56:59], off
	s_nop 1
	v_mov_b64_e32 v[56:57], v[178:179]
	v_mov_b64_e32 v[58:59], v[180:181]
	s_nop 0
	s_nop 1
	v_mov_b64_e32 v[60:61], v[182:183]
	v_mov_b64_e32 v[62:63], v[184:185]
	v_mul_f32_e32 v67, v67, v67
	v_mul_f32_e32 v69, v69, v69
	v_mul_f32_e32 v71, v71, v71
	v_mul_f32_e32 v73, v73, v73
	v_fmac_f32_e32 v67, v66, v66
	v_fmac_f32_e32 v69, v68, v68
	v_fmac_f32_e32 v71, v70, v70
	v_fmac_f32_e32 v73, v72, v72
	v_add_f32_e32 v66, v67, v69
	v_add_f32_e32 v67, v71, v73
	v_add_f32_e32 v66, v66, v67
	v_pk_add_f32 v[54:55], v[54:55], v[58:59]
	v_pk_add_f32 v[56:57], v[52:53], v[56:57]
	v_pk_add_f32 v[50:51], v[50:51], v[62:63]
	v_pk_add_f32 v[58:59], v[48:49], v[60:61]
	v_mul_f32_e32 v48, v57, v57
	v_mul_f32_e32 v49, v55, v55
	v_mul_f32_e32 v52, v59, v59
	v_mul_f32_e32 v53, v51, v51
	v_fmac_f32_e32 v48, v56, v56
	v_fmac_f32_e32 v49, v54, v54
	v_fmac_f32_e32 v52, v58, v58
	v_fmac_f32_e32 v53, v50, v50
	v_add_f32_e32 v48, v48, v49
	v_add_f32_e32 v49, v52, v53
	v_add_f32_e32 v48, v48, v49
	v_add_f32_e32 v48, v66, v48
	ds_bpermute_b32 v49, v175, v48
	v_cvt_pk_f16_f32 v53, v50, v51
	v_cvt_pk_f16_f32 v51, v54, v55
	v_cvt_pk_f16_f32 v52, v58, v59
	v_cvt_pk_f16_f32 v50, v56, v57
	s_waitcnt lgkmcnt(0)
	v_add_f32_e32 v48, v48, v49
	ds_bpermute_b32 v49, v177, v48
	global_store_dwordx4 v[74:75], v[50:53], off offset:256
	s_and_saveexec_b64 s[54:55], s[10:11]
	s_cbranch_execz .LBB0_912
	v_lshlrev_b64 v[50:51], 6, v[64:65]
	v_lshl_add_u64 v[50:51], s[16:17], 0, v[50:51]
	v_lshl_add_u64 v[50:51], s[52:53], 2, v[50:51]
	s_lshl_b32 s24, s80, 2
	v_lshl_add_u64 v[50:51], v[50:51], 0, s[24:25]
	s_waitcnt lgkmcnt(0)
	v_add_f32_e32 v48, v48, v49
	global_store_dword v[50:51], v48, off
;     __device__ __forceinline__ void operator()(const f32x4 (&acc)[2][2][4][2], const pg8::Unit& u, int wr, int wc, int fr, int fq) const {
;         const int row0 = u.pm * 256 + wr * 64 + fr, col0 = u.pn * 256 + 32 * wc + 8 * fq;
; #pragma unroll
;         for (int ai = 0; ai < 2; ++ai)
; #pragma unroll
;             for (int m = 0; m < 4; ++m) {
;                 const size_t row = (size_t)(row0 + ai * 128 + m * 16);
;                 float rstd = 1.f, ss = 0.f;
;                 if (MODE == 4) { const GAS f32x4* sp = (const GAS f32x4*)(SSR + row * 16); f32x4 s = (sp[0] + sp[1]) + (sp[2] + sp[3]);
;                     rstd = __builtin_amdgcn_rsqf(((s[0] + s[1]) + (s[2] + s[3])) * (1.f / 1024.f) + EPS); }
; #pragma unroll
;                 for (int bj = 0; bj < 2; ++bj) {
;                     const size_t off = row * 1024 + col0 + 128 * bj;
;                     const f32x4 a0 = acc[ai][bj][m][0], a1 = acc[ai][bj][m][1];
;                     if (MODE == 0) { f32x4 g0, g1; h8_to_f(*(const GAS h8*)(G16 + off), g0, g1); *(GAS h8*)(O16 + off) = pack8(g0 * a0, g1 * a1); }
;                     if (MODE == 1) { f32x4 g0, g1, p0, p1; h8_to_f(*(const GAS h8*)(G16 + off), g0, g1); h8_to_f(*(const GAS h8*)(O16 + off), p0, p1); *(GAS h8*)(O16 + off) = pack8(p0 + g0 * a0, p1 + g1 * a1); }
;                     if (MODE == 2) { const f32x4 x0 = __builtin_nontemporal_load((const GAS f32x4*)(RES + off)) + a0, x1 = __builtin_nontemporal_load((const GAS f32x4*)(RES + off + 4)) + a1;
;                         *(GAS h8*)(O16 + off) = pack8(x0, x1); ss += sq4(x0) + sq4(x1); }
;                     if (MODE == 5) { f32x4 r0, r1; h8_to_f(*(const GAS h8*)(R16 + off), r0, r1); const f32x4 x0 = r0 + a0, x1 = r1 + a1;
;                         *(GAS h8*)(O16 + off) = pack8(x0, x1); ss += sq4(x0) + sq4(x1); }
;                     if (MODE == 3) { *(GAS h8*)(O16 + off) = pack8(a0, a1); }
;                     if (MODE == 4) { f32x4 g0, g1; h8_to_f(*(const GAS h8*)(G16 + off), g0, g1);
;                         f32x4 r0, r1; h8_to_f(*(const GAS h8*)(R16 + off), r0, r1);
;                         const f32x4 x0 = r0 + sigm4(a0 * rstd) * g0, x1 = r1 + sigm4(a1 * rstd) * g1;
;                         __builtin_nontemporal_store(x0, (GAS f32x4*)(OUT + off)); __builtin_nontemporal_store(x1, (GAS f32x4*)(OUT + off + 4)); }
;                 }
.LBB0_912:
	s_or_b64 exec, exec, s[54:55]
	v_add_u32_e32 v48, 0x90, v146
	s_waitcnt lgkmcnt(0)
	v_ashrrev_i32_e32 v49, 31, v48
	v_lshlrev_b64 v[50:51], 10, v[48:49]
	v_lshl_add_u64 v[58:59], v[50:51], 0, v[144:145]
	v_lshl_add_u64 v[60:61], v[58:59], 2, s[18:19]
	s_waitcnt vmcnt(8)
	s_nop 1
	v_mov_b64_e32 v[50:51], v[186:187]
	v_mov_b64_e32 v[52:53], v[188:189]
	s_nop 1
	v_mov_b64_e32 v[54:55], v[190:191]
	v_mov_b64_e32 v[56:57], v[192:193]
	v_lshl_add_u64 v[58:59], v[58:59], 1, s[40:41]
	v_pk_add_f32 v[52:53], v[46:47], v[52:53]
	v_pk_add_f32 v[50:51], v[44:45], v[50:51]
	v_pk_add_f32 v[56:57], v[42:43], v[56:57]
	v_pk_add_f32 v[54:55], v[40:41], v[54:55]
	v_cvt_pk_f16_f32 v43, v56, v57
	v_cvt_pk_f16_f32 v41, v52, v53
	v_cvt_pk_f16_f32 v42, v54, v55
	v_cvt_pk_f16_f32 v40, v50, v51
	global_store_dwordx4 v[58:59], v[40:43], off
	s_nop 1
	v_mov_b64_e32 v[40:41], v[194:195]
	v_mov_b64_e32 v[42:43], v[196:197]
	s_nop 0
	s_nop 1
	v_mov_b64_e32 v[44:45], v[198:199]
	v_mov_b64_e32 v[46:47], v[200:201]
	v_mul_f32_e32 v51, v51, v51
	v_mul_f32_e32 v53, v53, v53
	v_mul_f32_e32 v55, v55, v55
	v_mul_f32_e32 v57, v57, v57
	v_fmac_f32_e32 v51, v50, v50
	v_fmac_f32_e32 v53, v52, v52
	v_fmac_f32_e32 v55, v54, v54
	v_fmac_f32_e32 v57, v56, v56
	v_add_f32_e32 v50, v51, v53
	v_add_f32_e32 v51, v55, v57
	v_add_f32_e32 v50, v50, v51
	v_pk_add_f32 v[38:39], v[38:39], v[42:43]
	v_pk_add_f32 v[40:41], v[36:37], v[40:41]
	v_pk_add_f32 v[34:35], v[34:35], v[46:47]
	v_pk_add_f32 v[42:43], v[32:33], v[44:45]
	v_mul_f32_e32 v32, v41, v41
	v_mul_f32_e32 v33, v39, v39
	v_mul_f32_e32 v36, v43, v43
	v_mul_f32_e32 v37, v35, v35
	v_fmac_f32_e32 v32, v40, v40
	v_fmac_f32_e32 v33, v38, v38
	v_fmac_f32_e32 v36, v42, v42
	v_fmac_f32_e32 v37, v34, v34
	v_add_f32_e32 v32, v32, v33
	v_add_f32_e32 v33, v36, v37
	v_add_f32_e32 v32, v32, v33
	v_add_f32_e32 v32, v50, v32
	ds_bpermute_b32 v33, v175, v32
	v_cvt_pk_f16_f32 v37, v34, v35
	v_cvt_pk_f16_f32 v35, v38, v39
	v_cvt_pk_f16_f32 v36, v42, v43
	v_cvt_pk_f16_f32 v34, v40, v41
	s_waitcnt lgkmcnt(0)
	v_add_f32_e32 v32, v32, v33
	ds_bpermute_b32 v33, v177, v32
	global_store_dwordx4 v[58:59], v[34:37], off offset:256
	s_and_saveexec_b64 s[54:55], s[10:11]
	s_cbranch_execz .LBB0_914
	v_lshlrev_b64 v[34:35], 6, v[48:49]
	v_lshl_add_u64 v[34:35], s[16:17], 0, v[34:35]
	v_lshl_add_u64 v[34:35], s[52:53], 2, v[34:35]
	s_lshl_b32 s24, s80, 2
	v_lshl_add_u64 v[34:35], v[34:35], 0, s[24:25]
	s_waitcnt lgkmcnt(0)
	v_add_f32_e32 v32, v32, v33
	global_store_dword v[34:35], v32, off
;     __device__ __forceinline__ void operator()(const f32x4 (&acc)[2][2][4][2], const pg8::Unit& u, int wr, int wc, int fr, int fq) const {
;         const int row0 = u.pm * 256 + wr * 64 + fr, col0 = u.pn * 256 + 32 * wc + 8 * fq;
; #pragma unroll
;         for (int ai = 0; ai < 2; ++ai)
; #pragma unroll
;             for (int m = 0; m < 4; ++m) {
;                 const size_t row = (size_t)(row0 + ai * 128 + m * 16);
;                 float rstd = 1.f, ss = 0.f;
;                 if (MODE == 4) { const GAS f32x4* sp = (const GAS f32x4*)(SSR + row * 16); f32x4 s = (sp[0] + sp[1]) + (sp[2] + sp[3]);
;                     rstd = __builtin_amdgcn_rsqf(((s[0] + s[1]) + (s[2] + s[3])) * (1.f / 1024.f) + EPS); }
; #pragma unroll
;                 for (int bj = 0; bj < 2; ++bj) {
;                     const size_t off = row * 1024 + col0 + 128 * bj;
;                     const f32x4 a0 = acc[ai][bj][m][0], a1 = acc[ai][bj][m][1];
;                     if (MODE == 0) { f32x4 g0, g1; h8_to_f(*(const GAS h8*)(G16 + off), g0, g1); *(GAS h8*)(O16 + off) = pack8(g0 * a0, g1 * a1); }
;                     if (MODE == 1) { f32x4 g0, g1, p0, p1; h8_to_f(*(const GAS h8*)(G16 + off), g0, g1); h8_to_f(*(const GAS h8*)(O16 + off), p0, p1); *(GAS h8*)(O16 + off) = pack8(p0 + g0 * a0, p1 + g1 * a1); }
;                     if (MODE == 2) { const f32x4 x0 = __builtin_nontemporal_load((const GAS f32x4*)(RES + off)) + a0, x1 = __builtin_nontemporal_load((const GAS f32x4*)(RES + off + 4)) + a1;
;                         *(GAS h8*)(O16 + off) = pack8(x0, x1); ss += sq4(x0) + sq4(x1); }
;                     if (MODE == 5) { f32x4 r0, r1; h8_to_f(*(const GAS h8*)(R16 + off), r0, r1); const f32x4 x0 = r0 + a0, x1 = r1 + a1;
;                         *(GAS h8*)(O16 + off) = pack8(x0, x1); ss += sq4(x0) + sq4(x1); }
;                     if (MODE == 3) { *(GAS h8*)(O16 + off) = pack8(a0, a1); }
;                     if (MODE == 4) { f32x4 g0, g1; h8_to_f(*(const GAS h8*)(G16 + off), g0, g1);
;                         f32x4 r0, r1; h8_to_f(*(const GAS h8*)(R16 + off), r0, r1);
;                         const f32x4 x0 = r0 + sigm4(a0 * rstd) * g0, x1 = r1 + sigm4(a1 * rstd) * g1;
;                         __builtin_nontemporal_store(x0, (GAS f32x4*)(OUT + off)); __builtin_nontemporal_store(x1, (GAS f32x4*)(OUT + off + 4)); }
;                 }
.LBB0_914:
	s_or_b64 exec, exec, s[54:55]
	v_add_u32_e32 v32, 0xa0, v146
	s_waitcnt lgkmcnt(0)
	v_ashrrev_i32_e32 v33, 31, v32
	v_lshlrev_b64 v[34:35], 10, v[32:33]
	v_lshl_add_u64 v[42:43], v[34:35], 0, v[144:145]
	v_lshl_add_u64 v[44:45], v[42:43], 2, s[18:19]
	s_waitcnt vmcnt(4)
	s_nop 1
	v_mov_b64_e32 v[34:35], v[202:203]
	v_mov_b64_e32 v[36:37], v[204:205]
	s_nop 1
	v_mov_b64_e32 v[38:39], v[206:207]
	v_mov_b64_e32 v[40:41], v[208:209]
	v_lshl_add_u64 v[42:43], v[42:43], 1, s[40:41]
	v_pk_add_f32 v[36:37], v[30:31], v[36:37]
	v_pk_add_f32 v[34:35], v[28:29], v[34:35]
	v_pk_add_f32 v[40:41], v[26:27], v[40:41]
	v_pk_add_f32 v[38:39], v[24:25], v[38:39]
	v_cvt_pk_f16_f32 v27, v40, v41
	v_cvt_pk_f16_f32 v25, v36, v37
	v_cvt_pk_f16_f32 v26, v38, v39
	v_cvt_pk_f16_f32 v24, v34, v35
	global_store_dwordx4 v[42:43], v[24:27], off
	s_nop 1
	v_mov_b64_e32 v[24:25], v[210:211]
	v_mov_b64_e32 v[26:27], v[212:213]
	s_nop 0
	s_nop 1
	v_mov_b64_e32 v[28:29], v[214:215]
	v_mov_b64_e32 v[30:31], v[216:217]
	v_mul_f32_e32 v35, v35, v35
	v_mul_f32_e32 v37, v37, v37
	v_mul_f32_e32 v39, v39, v39
	v_mul_f32_e32 v41, v41, v41
	v_fmac_f32_e32 v35, v34, v34
	v_fmac_f32_e32 v37, v36, v36
	v_fmac_f32_e32 v39, v38, v38
	v_fmac_f32_e32 v41, v40, v40
	v_add_f32_e32 v34, v35, v37
	v_add_f32_e32 v35, v39, v41
	v_add_f32_e32 v34, v34, v35
	v_pk_add_f32 v[22:23], v[22:23], v[26:27]
	v_pk_add_f32 v[24:25], v[20:21], v[24:25]
	v_pk_add_f32 v[18:19], v[18:19], v[30:31]
	v_pk_add_f32 v[26:27], v[16:17], v[28:29]
	v_mul_f32_e32 v16, v25, v25
	v_mul_f32_e32 v17, v23, v23
	v_mul_f32_e32 v20, v27, v27
	v_mul_f32_e32 v21, v19, v19
	v_fmac_f32_e32 v16, v24, v24
	v_fmac_f32_e32 v17, v22, v22
	v_fmac_f32_e32 v20, v26, v26
	v_fmac_f32_e32 v21, v18, v18
	v_add_f32_e32 v16, v16, v17
	v_add_f32_e32 v17, v20, v21
	v_add_f32_e32 v16, v16, v17
	v_add_f32_e32 v16, v34, v16
	ds_bpermute_b32 v17, v175, v16
	v_cvt_pk_f16_f32 v21, v18, v19
	v_cvt_pk_f16_f32 v19, v22, v23
	v_cvt_pk_f16_f32 v20, v26, v27
	v_cvt_pk_f16_f32 v18, v24, v25
	s_waitcnt lgkmcnt(0)
	v_add_f32_e32 v16, v16, v17
	ds_bpermute_b32 v17, v177, v16
	global_store_dwordx4 v[42:43], v[18:21], off offset:256
	s_and_saveexec_b64 s[54:55], s[10:11]
	s_cbranch_execz .LBB0_916
	v_lshlrev_b64 v[18:19], 6, v[32:33]
	v_lshl_add_u64 v[18:19], s[16:17], 0, v[18:19]
	v_lshl_add_u64 v[18:19], s[52:53], 2, v[18:19]
	s_lshl_b32 s24, s80, 2
	v_lshl_add_u64 v[18:19], v[18:19], 0, s[24:25]
	s_waitcnt lgkmcnt(0)
	v_add_f32_e32 v16, v16, v17
	global_store_dword v[18:19], v16, off
.LBB0_916:
	s_or_b64 exec, exec, s[54:55]
	v_add_u32_e32 v16, 0xb0, v146
	s_waitcnt lgkmcnt(0)
	v_ashrrev_i32_e32 v17, 31, v16
	v_lshlrev_b64 v[18:19], 10, v[16:17]
	v_lshl_add_u64 v[26:27], v[18:19], 0, v[144:145]
	v_lshl_add_u64 v[28:29], v[26:27], 2, s[18:19]
	s_waitcnt vmcnt(0)
	s_nop 1
	v_mov_b64_e32 v[18:19], v[218:219]
	v_mov_b64_e32 v[20:21], v[220:221]
	s_nop 1
	v_mov_b64_e32 v[22:23], v[222:223]
	v_mov_b64_e32 v[24:25], v[224:225]
	v_lshl_add_u64 v[26:27], v[26:27], 1, s[40:41]
	v_pk_add_f32 v[20:21], v[14:15], v[20:21]
	v_pk_add_f32 v[18:19], v[12:13], v[18:19]
	v_pk_add_f32 v[24:25], v[10:11], v[24:25]
	v_pk_add_f32 v[22:23], v[8:9], v[22:23]
	v_cvt_pk_f16_f32 v11, v24, v25
	v_cvt_pk_f16_f32 v9, v20, v21
	v_cvt_pk_f16_f32 v10, v22, v23
	v_cvt_pk_f16_f32 v8, v18, v19
	global_store_dwordx4 v[26:27], v[8:11], off
	s_nop 1
	v_mov_b64_e32 v[8:9], v[226:227]
	v_mov_b64_e32 v[10:11], v[228:229]
	s_nop 0
	s_nop 1
	v_mov_b64_e32 v[12:13], v[230:231]
	v_mov_b64_e32 v[14:15], v[232:233]
	v_mul_f32_e32 v19, v19, v19
	v_mul_f32_e32 v21, v21, v21
	v_mul_f32_e32 v23, v23, v23
	v_mul_f32_e32 v25, v25, v25
	v_fmac_f32_e32 v19, v18, v18
	v_fmac_f32_e32 v21, v20, v20
	v_fmac_f32_e32 v23, v22, v22
	v_fmac_f32_e32 v25, v24, v24
	v_add_f32_e32 v18, v19, v21
	v_add_f32_e32 v19, v23, v25
	v_add_f32_e32 v18, v18, v19
	v_pk_add_f32 v[6:7], v[6:7], v[10:11]
	v_pk_add_f32 v[8:9], v[4:5], v[8:9]
	v_pk_add_f32 v[2:3], v[2:3], v[14:15]
	v_pk_add_f32 v[10:11], v[0:1], v[12:13]
	v_mul_f32_e32 v0, v9, v9
	v_mul_f32_e32 v1, v7, v7
	v_mul_f32_e32 v4, v11, v11
	v_mul_f32_e32 v5, v3, v3
	v_fmac_f32_e32 v0, v8, v8
	v_fmac_f32_e32 v1, v6, v6
	v_fmac_f32_e32 v4, v10, v10
	v_fmac_f32_e32 v5, v2, v2
	v_add_f32_e32 v0, v0, v1
	v_add_f32_e32 v1, v4, v5
	v_add_f32_e32 v0, v0, v1
	v_add_f32_e32 v0, v18, v0
	ds_bpermute_b32 v1, v175, v0
	v_cvt_pk_f16_f32 v5, v2, v3
	v_cvt_pk_f16_f32 v3, v6, v7
	v_cvt_pk_f16_f32 v4, v10, v11
	v_cvt_pk_f16_f32 v2, v8, v9
	s_waitcnt lgkmcnt(0)
	v_add_f32_e32 v0, v0, v1
	ds_bpermute_b32 v1, v177, v0
	global_store_dwordx4 v[26:27], v[2:5], off offset:256
	s_and_saveexec_b64 s[54:55], s[10:11]
	s_cbranch_execz .LBB0_918
	v_lshlrev_b64 v[2:3], 6, v[16:17]
	v_lshl_add_u64 v[2:3], s[16:17], 0, v[2:3]
	v_lshl_add_u64 v[2:3], s[52:53], 2, v[2:3]
	s_lshl_b32 s24, s80, 2
	v_lshl_add_u64 v[2:3], v[2:3], 0, s[24:25]
	s_waitcnt lgkmcnt(0)
	v_add_f32_e32 v0, v0, v1
	global_store_dword v[2:3], v0, off

; __global__ void __launch_bounds__(512) mega_fwd(Params P_) {
	.amdhsa_kernel _Z8mega_fwd6Params
		.amdhsa_group_segment_fixed_size 0
		.amdhsa_private_segment_fixed_size 0
		.amdhsa_kernarg_size 432
		.amdhsa_user_sgpr_count 2
		.amdhsa_user_sgpr_dispatch_ptr 0
		.amdhsa_user_sgpr_queue_ptr 0
		.amdhsa_user_sgpr_kernarg_segment_ptr 1
		.amdhsa_user_sgpr_dispatch_id 0
		.amdhsa_user_sgpr_kernarg_preload_length 0
		.amdhsa_user_sgpr_kernarg_preload_offset 0
		.amdhsa_user_sgpr_private_segment_size 0
		.amdhsa_uses_dynamic_stack 0
		.amdhsa_enable_private_segment 0
		.amdhsa_system_sgpr_workgroup_id_x 1
		.amdhsa_system_sgpr_workgroup_id_y 0
		.amdhsa_system_sgpr_workgroup_id_z 0
		.amdhsa_system_sgpr_workgroup_info 0
		.amdhsa_system_vgpr_workitem_id 2
		.amdhsa_next_free_vgpr 256
		.amdhsa_next_free_sgpr 98
		.amdhsa_accum_offset 256
		.amdhsa_reserve_vcc 1
		.amdhsa_float_round_mode_32 0
		.amdhsa_float_round_mode_16_64 0
		.amdhsa_float_denorm_mode_32 3
		.amdhsa_float_denorm_mode_16_64 3
		.amdhsa_dx10_clamp 1
		.amdhsa_ieee_mode 1
		.amdhsa_fp16_overflow 0
		.amdhsa_tg_split 0
		.amdhsa_exception_fp_ieee_invalid_op 0
		.amdhsa_exception_fp_denorm_src 0
		.amdhsa_exception_fp_ieee_div_zero 0
		.amdhsa_exception_fp_ieee_overflow 0
		.amdhsa_exception_fp_ieee_underflow 0
		.amdhsa_exception_fp_ieee_inexact 0
		.amdhsa_exception_int_div_zero 0
	.end_amdhsa_kernel

; __global__ void __launch_bounds__(512) mega_fwd(Params P_) {
amdhsa.kernels:
  - .agpr_count:     0
    .args:
      - .offset:         0
        .size:           176
        .value_kind:     by_value
      - .offset:         176
        .size:           4
        .value_kind:     hidden_block_count_x
      - .offset:         180
        .size:           4
        .value_kind:     hidden_block_count_y
      - .offset:         184
        .size:           4
        .value_kind:     hidden_block_count_z
      - .offset:         188
        .size:           2
        .value_kind:     hidden_group_size_x
      - .offset:         190
        .size:           2
        .value_kind:     hidden_group_size_y
      - .offset:         192
        .size:           2
        .value_kind:     hidden_group_size_z
      - .offset:         194
        .size:           2
        .value_kind:     hidden_remainder_x
      - .offset:         196
        .size:           2
        .value_kind:     hidden_remainder_y
      - .offset:         198
        .size:           2
        .value_kind:     hidden_remainder_z
      - .offset:         216
        .size:           8
        .value_kind:     hidden_global_offset_x
      - .offset:         224
        .size:           8
        .value_kind:     hidden_global_offset_y
      - .offset:         232
        .size:           8
        .value_kind:     hidden_global_offset_z
      - .offset:         240
        .size:           2
        .value_kind:     hidden_grid_dims
      - .offset:         264
        .size:           8
        .value_kind:     hidden_multigrid_sync_arg
      - .offset:         296
        .size:           4
        .value_kind:     hidden_dynamic_lds_size
    .group_segment_fixed_size: 0
    .kernarg_segment_align: 8
    .kernarg_segment_size: 432
    .language:       OpenCL C
    .language_version:
      - 2
      - 0
    .max_flat_workgroup_size: 512
    .name:           _Z8mega_fwd6Params
    .private_segment_fixed_size: 0
    .sgpr_count:     104
    .sgpr_spill_count: 14
    .symbol:         _Z8mega_fwd6Params.kd
    .uniform_work_group_size: 1
    .uses_dynamic_stack: false
    .vgpr_count:     256
    .vgpr_spill_count: 0
    .wavefront_size: 64
